# prologue x conversion: two units per step with two steps of loads in flight
# speedup vs baseline: 1.0063x; 1.0063x over previous
.LBB0_54:
	v_lshlrev_b32_e32 v10, 5, v178
	v_lshlrev_b32_e32 v11, 4, v178
	s_add_i32 s4, s56, -1728
	s_cmpk_lt_u32 s4, 0x1000
	s_cselect_b32 s34, s12, s14
	s_cselect_b32 s35, s13, s15
	s_cselect_b32 s2, 0, 0x1000
	s_sub_i32 s2, s4, s2
	s_lshl_b32 s2, s2, 14
	s_add_u32 s34, s34, s2
	s_addc_u32 s35, s35, 0
	s_lshl_b32 s2, s4, 13
	s_add_u32 s36, s0, s2
	s_addc_u32 s37, s1, 0
	global_load_dwordx4 v[0:3], v10, s[34:35]
	global_load_dwordx4 v[12:15], v10, s[34:35] offset:16
	s_add_i32 s4, s56, -1472
	s_cmpk_lt_u32 s4, 0x1000
	s_cselect_b32 s34, s12, s14
	s_cselect_b32 s35, s13, s15
	s_cselect_b32 s2, 0, 0x1000
	s_sub_i32 s2, s4, s2
	s_lshl_b32 s2, s2, 14
	s_add_u32 s34, s34, s2
	s_addc_u32 s35, s35, 0
	s_lshl_b32 s2, s4, 13
	s_add_u32 s38, s0, s2
	s_addc_u32 s39, s1, 0
	global_load_dwordx4 v[16:19], v10, s[34:35]
	global_load_dwordx4 v[20:23], v10, s[34:35] offset:16
	s_add_i32 s4, s56, -1216
	s_cmpk_lt_u32 s4, 0x1000
	s_cselect_b32 s34, s12, s14
	s_cselect_b32 s35, s13, s15
	s_cselect_b32 s2, 0, 0x1000
	s_sub_i32 s2, s4, s2
	s_lshl_b32 s2, s2, 14
	s_add_u32 s34, s34, s2
	s_addc_u32 s35, s35, 0
	s_lshl_b32 s2, s4, 13
	s_add_u32 s40, s0, s2
	s_addc_u32 s41, s1, 0
	global_load_dwordx4 v[24:27], v10, s[34:35]
	global_load_dwordx4 v[244:247], v10, s[34:35] offset:16
	s_add_i32 s4, s56, -960
	s_cmpk_lt_u32 s4, 0x1000
	s_cselect_b32 s34, s12, s14
	s_cselect_b32 s35, s13, s15
	s_cselect_b32 s2, 0, 0x1000
	s_sub_i32 s2, s4, s2
	s_lshl_b32 s2, s2, 14
	s_add_u32 s34, s34, s2
	s_addc_u32 s35, s35, 0
	s_lshl_b32 s2, s4, 13
	s_add_u32 s42, s0, s2
	s_addc_u32 s43, s1, 0
	global_load_dwordx4 v[248:251], v10, s[34:35]
	global_load_dwordx4 v[252:255], v10, s[34:35] offset:16
	s_waitcnt vmcnt(4)
	v_cvt_pk_bf16_f32 v0, v0, v1
	v_cvt_pk_bf16_f32 v1, v2, v3
	v_cvt_pk_bf16_f32 v2, v12, v13
	v_cvt_pk_bf16_f32 v3, v14, v15
	global_store_dwordx4 v11, v[0:3], s[36:37]
	v_cvt_pk_bf16_f32 v16, v16, v17
	v_cvt_pk_bf16_f32 v17, v18, v19
	v_cvt_pk_bf16_f32 v18, v20, v21
	v_cvt_pk_bf16_f32 v19, v22, v23
	global_store_dwordx4 v11, v[16:19], s[38:39]
	s_nop 1
	s_add_i32 s4, s56, -704
	s_cmpk_lt_u32 s4, 0x1000
	s_cselect_b32 s34, s12, s14
	s_cselect_b32 s35, s13, s15
	s_cselect_b32 s2, 0, 0x1000
	s_sub_i32 s2, s4, s2
	s_lshl_b32 s2, s2, 14
	s_add_u32 s34, s34, s2
	s_addc_u32 s35, s35, 0
	s_lshl_b32 s2, s4, 13
	s_add_u32 s36, s0, s2
	s_addc_u32 s37, s1, 0
	global_load_dwordx4 v[0:3], v10, s[34:35]
	global_load_dwordx4 v[12:15], v10, s[34:35] offset:16
	s_add_i32 s4, s56, -448
	s_cmpk_lt_u32 s4, 0x1000
	s_cselect_b32 s34, s12, s14
	s_cselect_b32 s35, s13, s15
	s_cselect_b32 s2, 0, 0x1000
	s_sub_i32 s2, s4, s2
	s_lshl_b32 s2, s2, 14
	s_add_u32 s34, s34, s2
	s_addc_u32 s35, s35, 0
	s_lshl_b32 s2, s4, 13
	s_add_u32 s38, s0, s2
	s_addc_u32 s39, s1, 0
	global_load_dwordx4 v[16:19], v10, s[34:35]
	global_load_dwordx4 v[20:23], v10, s[34:35] offset:16
	s_waitcnt vmcnt(6)
	v_cvt_pk_bf16_f32 v24, v24, v25
	v_cvt_pk_bf16_f32 v25, v26, v27
	v_cvt_pk_bf16_f32 v26, v244, v245
	v_cvt_pk_bf16_f32 v27, v246, v247
	global_store_dwordx4 v11, v[24:27], s[40:41]
	v_cvt_pk_bf16_f32 v248, v248, v249
	v_cvt_pk_bf16_f32 v249, v250, v251
	v_cvt_pk_bf16_f32 v250, v252, v253
	v_cvt_pk_bf16_f32 v251, v254, v255
	global_store_dwordx4 v11, v[248:251], s[42:43]
	s_nop 1
	s_add_i32 s4, s56, -192
	s_cmpk_lt_u32 s4, 0x1000
	s_cselect_b32 s34, s12, s14
	s_cselect_b32 s35, s13, s15
	s_cselect_b32 s2, 0, 0x1000
	s_sub_i32 s2, s4, s2
	s_lshl_b32 s2, s2, 14
	s_add_u32 s34, s34, s2
	s_addc_u32 s35, s35, 0
	s_lshl_b32 s2, s4, 13
	s_add_u32 s40, s0, s2
	s_addc_u32 s41, s1, 0
	global_load_dwordx4 v[24:27], v10, s[34:35]
	global_load_dwordx4 v[244:247], v10, s[34:35] offset:16
	s_add_i32 s4, s56, 64
	s_cmpk_lt_u32 s4, 0x1000
	s_cselect_b32 s34, s12, s14
	s_cselect_b32 s35, s13, s15
	s_cselect_b32 s2, 0, 0x1000
	s_sub_i32 s2, s4, s2
	s_lshl_b32 s2, s2, 14
	s_add_u32 s34, s34, s2
	s_addc_u32 s35, s35, 0
	s_lshl_b32 s2, s4, 13
	s_add_u32 s42, s0, s2
	s_addc_u32 s43, s1, 0
	global_load_dwordx4 v[248:251], v10, s[34:35]
	global_load_dwordx4 v[252:255], v10, s[34:35] offset:16
	s_waitcnt vmcnt(6)
	v_cvt_pk_bf16_f32 v0, v0, v1
	v_cvt_pk_bf16_f32 v1, v2, v3
	v_cvt_pk_bf16_f32 v2, v12, v13
	v_cvt_pk_bf16_f32 v3, v14, v15
	global_store_dwordx4 v11, v[0:3], s[36:37]
	v_cvt_pk_bf16_f32 v16, v16, v17
	v_cvt_pk_bf16_f32 v17, v18, v19
	v_cvt_pk_bf16_f32 v18, v20, v21
	v_cvt_pk_bf16_f32 v19, v22, v23
	global_store_dwordx4 v11, v[16:19], s[38:39]
	s_nop 1
	s_add_i32 s4, s56, 320
	s_cmpk_lt_u32 s4, 0x1000
	s_cselect_b32 s34, s12, s14
	s_cselect_b32 s35, s13, s15
	s_cselect_b32 s2, 0, 0x1000
	s_sub_i32 s2, s4, s2
	s_lshl_b32 s2, s2, 14
	s_add_u32 s34, s34, s2
	s_addc_u32 s35, s35, 0
	s_lshl_b32 s2, s4, 13
	s_add_u32 s36, s0, s2
	s_addc_u32 s37, s1, 0
	global_load_dwordx4 v[0:3], v10, s[34:35]
	global_load_dwordx4 v[12:15], v10, s[34:35] offset:16
	s_add_i32 s4, s56, 576
	s_cmpk_lt_u32 s4, 0x1000
	s_cselect_b32 s34, s12, s14
	s_cselect_b32 s35, s13, s15
	s_cselect_b32 s2, 0, 0x1000
	s_sub_i32 s2, s4, s2
	s_lshl_b32 s2, s2, 14
	s_add_u32 s34, s34, s2
	s_addc_u32 s35, s35, 0
	s_lshl_b32 s2, s4, 13
	s_add_u32 s38, s0, s2
	s_addc_u32 s39, s1, 0
	global_load_dwordx4 v[16:19], v10, s[34:35]
	global_load_dwordx4 v[20:23], v10, s[34:35] offset:16
	s_waitcnt vmcnt(6)
	v_cvt_pk_bf16_f32 v24, v24, v25
	v_cvt_pk_bf16_f32 v25, v26, v27
	v_cvt_pk_bf16_f32 v26, v244, v245
	v_cvt_pk_bf16_f32 v27, v246, v247
	global_store_dwordx4 v11, v[24:27], s[40:41]
	v_cvt_pk_bf16_f32 v248, v248, v249
	v_cvt_pk_bf16_f32 v249, v250, v251
	v_cvt_pk_bf16_f32 v250, v252, v253
	v_cvt_pk_bf16_f32 v251, v254, v255
	global_store_dwordx4 v11, v[248:251], s[42:43]
	s_nop 1
	s_add_i32 s4, s56, 832
	s_cmpk_lt_u32 s4, 0x1000
	s_cselect_b32 s34, s12, s14
	s_cselect_b32 s35, s13, s15
	s_cselect_b32 s2, 0, 0x1000
	s_sub_i32 s2, s4, s2
	s_lshl_b32 s2, s2, 14
	s_add_u32 s34, s34, s2
	s_addc_u32 s35, s35, 0
	s_lshl_b32 s2, s4, 13
	s_add_u32 s40, s0, s2
	s_addc_u32 s41, s1, 0
	global_load_dwordx4 v[24:27], v10, s[34:35]
	global_load_dwordx4 v[244:247], v10, s[34:35] offset:16
	s_add_i32 s4, s56, 1088
	s_cmpk_lt_u32 s4, 0x1000
	s_cselect_b32 s34, s12, s14
	s_cselect_b32 s35, s13, s15
	s_cselect_b32 s2, 0, 0x1000
	s_sub_i32 s2, s4, s2
	s_lshl_b32 s2, s2, 14
	s_add_u32 s34, s34, s2
	s_addc_u32 s35, s35, 0
	s_lshl_b32 s2, s4, 13
	s_add_u32 s42, s0, s2
	s_addc_u32 s43, s1, 0
	global_load_dwordx4 v[248:251], v10, s[34:35]
	global_load_dwordx4 v[252:255], v10, s[34:35] offset:16
	s_waitcnt vmcnt(6)
	v_cvt_pk_bf16_f32 v0, v0, v1
	v_cvt_pk_bf16_f32 v1, v2, v3
	v_cvt_pk_bf16_f32 v2, v12, v13
	v_cvt_pk_bf16_f32 v3, v14, v15
	global_store_dwordx4 v11, v[0:3], s[36:37]
	v_cvt_pk_bf16_f32 v16, v16, v17
	v_cvt_pk_bf16_f32 v17, v18, v19
	v_cvt_pk_bf16_f32 v18, v20, v21
	v_cvt_pk_bf16_f32 v19, v22, v23
	global_store_dwordx4 v11, v[16:19], s[38:39]
	s_nop 1
	s_add_i32 s4, s56, 1344
	s_cmpk_lt_u32 s4, 0x1000
	s_cselect_b32 s34, s12, s14
	s_cselect_b32 s35, s13, s15
	s_cselect_b32 s2, 0, 0x1000
	s_sub_i32 s2, s4, s2
	s_lshl_b32 s2, s2, 14
	s_add_u32 s34, s34, s2
	s_addc_u32 s35, s35, 0
	s_lshl_b32 s2, s4, 13
	s_add_u32 s36, s0, s2
	s_addc_u32 s37, s1, 0
	global_load_dwordx4 v[0:3], v10, s[34:35]
	global_load_dwordx4 v[12:15], v10, s[34:35] offset:16
	s_add_i32 s4, s56, 1600
	s_cmpk_lt_u32 s4, 0x1000
	s_cselect_b32 s34, s12, s14
	s_cselect_b32 s35, s13, s15
	s_cselect_b32 s2, 0, 0x1000
	s_sub_i32 s2, s4, s2
	s_lshl_b32 s2, s2, 14
	s_add_u32 s34, s34, s2
	s_addc_u32 s35, s35, 0
	s_lshl_b32 s2, s4, 13
	s_add_u32 s38, s0, s2
	s_addc_u32 s39, s1, 0
	global_load_dwordx4 v[16:19], v10, s[34:35]
	global_load_dwordx4 v[20:23], v10, s[34:35] offset:16
	s_waitcnt vmcnt(6)
	v_cvt_pk_bf16_f32 v24, v24, v25
	v_cvt_pk_bf16_f32 v25, v26, v27
	v_cvt_pk_bf16_f32 v26, v244, v245
	v_cvt_pk_bf16_f32 v27, v246, v247
	global_store_dwordx4 v11, v[24:27], s[40:41]
	v_cvt_pk_bf16_f32 v248, v248, v249
	v_cvt_pk_bf16_f32 v249, v250, v251
	v_cvt_pk_bf16_f32 v250, v252, v253
	v_cvt_pk_bf16_f32 v251, v254, v255
	global_store_dwordx4 v11, v[248:251], s[42:43]
	s_nop 1
	s_add_i32 s4, s56, 1856
	s_cmpk_lt_u32 s4, 0x1000
	s_cselect_b32 s34, s12, s14
	s_cselect_b32 s35, s13, s15
	s_cselect_b32 s2, 0, 0x1000
	s_sub_i32 s2, s4, s2
	s_lshl_b32 s2, s2, 14
	s_add_u32 s34, s34, s2
	s_addc_u32 s35, s35, 0
	s_lshl_b32 s2, s4, 13
	s_add_u32 s40, s0, s2
	s_addc_u32 s41, s1, 0
	global_load_dwordx4 v[24:27], v10, s[34:35]
	global_load_dwordx4 v[244:247], v10, s[34:35] offset:16
	s_add_i32 s4, s56, 2112
	s_cmpk_lt_u32 s4, 0x1000
	s_cselect_b32 s34, s12, s14
	s_cselect_b32 s35, s13, s15
	s_cselect_b32 s2, 0, 0x1000
	s_sub_i32 s2, s4, s2
	s_lshl_b32 s2, s2, 14
	s_add_u32 s34, s34, s2
	s_addc_u32 s35, s35, 0
	s_lshl_b32 s2, s4, 13
	s_add_u32 s42, s0, s2
	s_addc_u32 s43, s1, 0
	global_load_dwordx4 v[248:251], v10, s[34:35]
	global_load_dwordx4 v[252:255], v10, s[34:35] offset:16
	s_waitcnt vmcnt(6)
	v_cvt_pk_bf16_f32 v0, v0, v1
	v_cvt_pk_bf16_f32 v1, v2, v3
	v_cvt_pk_bf16_f32 v2, v12, v13
	v_cvt_pk_bf16_f32 v3, v14, v15
	global_store_dwordx4 v11, v[0:3], s[36:37]
	v_cvt_pk_bf16_f32 v16, v16, v17
	v_cvt_pk_bf16_f32 v17, v18, v19
	v_cvt_pk_bf16_f32 v18, v20, v21
	v_cvt_pk_bf16_f32 v19, v22, v23
	global_store_dwordx4 v11, v[16:19], s[38:39]
	s_nop 1
	s_add_i32 s4, s56, 2368
	s_cmpk_lt_u32 s4, 0x1000
	s_cselect_b32 s34, s12, s14
	s_cselect_b32 s35, s13, s15
	s_cselect_b32 s2, 0, 0x1000
	s_sub_i32 s2, s4, s2
	s_lshl_b32 s2, s2, 14
	s_add_u32 s34, s34, s2
	s_addc_u32 s35, s35, 0
	s_lshl_b32 s2, s4, 13
	s_add_u32 s36, s0, s2
	s_addc_u32 s37, s1, 0
	global_load_dwordx4 v[0:3], v10, s[34:35]
	global_load_dwordx4 v[12:15], v10, s[34:35] offset:16
	s_add_i32 s4, s56, 2624
	s_cmpk_lt_u32 s4, 0x1000
	s_cselect_b32 s34, s12, s14
	s_cselect_b32 s35, s13, s15
	s_cselect_b32 s2, 0, 0x1000
	s_sub_i32 s2, s4, s2
	s_lshl_b32 s2, s2, 14
	s_add_u32 s34, s34, s2
	s_addc_u32 s35, s35, 0
	s_lshl_b32 s2, s4, 13
	s_add_u32 s38, s0, s2
	s_addc_u32 s39, s1, 0
	global_load_dwordx4 v[16:19], v10, s[34:35]
	global_load_dwordx4 v[20:23], v10, s[34:35] offset:16
	s_waitcnt vmcnt(6)
	v_cvt_pk_bf16_f32 v24, v24, v25
	v_cvt_pk_bf16_f32 v25, v26, v27
	v_cvt_pk_bf16_f32 v26, v244, v245
	v_cvt_pk_bf16_f32 v27, v246, v247
	global_store_dwordx4 v11, v[24:27], s[40:41]
	v_cvt_pk_bf16_f32 v248, v248, v249
	v_cvt_pk_bf16_f32 v249, v250, v251
	v_cvt_pk_bf16_f32 v250, v252, v253
	v_cvt_pk_bf16_f32 v251, v254, v255
	global_store_dwordx4 v11, v[248:251], s[42:43]
	s_nop 1
	s_waitcnt vmcnt(2)
	v_cvt_pk_bf16_f32 v0, v0, v1
	v_cvt_pk_bf16_f32 v1, v2, v3
	v_cvt_pk_bf16_f32 v2, v12, v13
	v_cvt_pk_bf16_f32 v3, v14, v15
	global_store_dwordx4 v11, v[0:3], s[36:37]
	v_cvt_pk_bf16_f32 v16, v16, v17
	v_cvt_pk_bf16_f32 v17, v18, v19
	v_cvt_pk_bf16_f32 v18, v20, v21
	v_cvt_pk_bf16_f32 v19, v22, v23
	global_store_dwordx4 v11, v[16:19], s[38:39]
	s_nop 1
	s_branch .LBB0_63
